# P8 (w_out GEMM) residual epilogue rewritten by hand: per-row-group pipeline with five groups of base loads in flight instead of two serial halves
# baseline (speedup 1.0000x reference)
.LBB0_1028:
	ds_read_b128 v[128:131], v240
	ds_read_b128 v[132:135], v240 offset:1024
	ds_read_b128 v[136:139], v240 offset:2048
	ds_read_b128 v[140:143], v240 offset:3072
	ds_read_b128 v[144:147], v241
	ds_read_b128 v[148:151], v241 offset:1024
	ds_read_b128 v[152:155], v241 offset:2048
	ds_read_b128 v[156:159], v241 offset:3072
	s_add_u32 s24, s22, 0xfffc0080
	s_addc_u32 s25, s23, -1
	s_cmp_eq_u32 s50, 12
	s_cselect_b32 s27, s17, s25
	s_cselect_b32 s26, s46, s24
	s_cselect_b32 s25, s15, s49
	s_cselect_b32 s24, s47, s48
	v_lshl_add_u64 v[192:193], s[22:23], 0, v[218:219]
	s_add_i32 m0, s34, 0xc000
	ds_read_b128 v[160:163], v242
	ds_read_b128 v[164:167], v242 offset:1024
	ds_read_b128 v[168:171], v242 offset:2048
	ds_read_b128 v[172:175], v242 offset:3072
	ds_read_b128 v[176:179], v242 offset:4096
	ds_read_b128 v[180:183], v242 offset:5120
	ds_read_b128 v[184:187], v242 offset:6144
	ds_read_b128 v[188:191], v242 offset:7168
	global_load_lds_dwordx4 v[192:193], off
	v_lshl_add_u64 v[192:193], s[22:23], 0, v[220:221]
	s_add_i32 m0, s34, 0xe000
	s_nop 0
	global_load_lds_dwordx4 v[192:193], off
	s_waitcnt vmcnt(8)
	s_waitcnt lgkmcnt(0)
	s_barrier
	s_setprio 1
	s_waitcnt lgkmcnt(0)
	v_mfma_f32_16x16x32_bf16 v[124:127], v[128:131], v[160:163], v[124:127]
	v_mfma_f32_16x16x32_bf16 v[120:123], v[136:139], v[160:163], v[120:123]
	v_mfma_f32_16x16x32_bf16 v[112:115], v[128:131], v[168:171], v[112:115]
	v_mfma_f32_16x16x32_bf16 v[104:107], v[136:139], v[168:171], v[104:107]
	v_mfma_f32_16x16x32_bf16 v[96:99], v[128:131], v[176:179], v[96:99]
	v_mfma_f32_16x16x32_bf16 v[88:91], v[136:139], v[176:179], v[88:91]
	v_mfma_f32_16x16x32_bf16 v[76:79], v[128:131], v[184:187], v[76:79]
	v_mfma_f32_16x16x32_bf16 v[72:75], v[136:139], v[184:187], v[72:75]
	v_mfma_f32_16x16x32_bf16 v[124:127], v[132:135], v[164:167], v[124:127]
	v_mfma_f32_16x16x32_bf16 v[120:123], v[140:143], v[164:167], v[120:123]
	v_mfma_f32_16x16x32_bf16 v[112:115], v[132:135], v[172:175], v[112:115]
	v_mfma_f32_16x16x32_bf16 v[104:107], v[140:143], v[172:175], v[104:107]
	v_mfma_f32_16x16x32_bf16 v[96:99], v[132:135], v[180:183], v[96:99]
	v_mfma_f32_16x16x32_bf16 v[88:91], v[140:143], v[180:183], v[88:91]
	v_mfma_f32_16x16x32_bf16 v[76:79], v[132:135], v[188:191], v[76:79]
	v_mfma_f32_16x16x32_bf16 v[72:75], v[140:143], v[188:191], v[72:75]
	v_mfma_f32_16x16x32_bf16 v[116:119], v[144:147], v[160:163], v[116:119]
	v_mfma_f32_16x16x32_bf16 v[108:111], v[152:155], v[160:163], v[108:111]
	v_mfma_f32_16x16x32_bf16 v[100:103], v[144:147], v[168:171], v[100:103]
	v_mfma_f32_16x16x32_bf16 v[92:95], v[152:155], v[168:171], v[92:95]
	v_mfma_f32_16x16x32_bf16 v[84:87], v[144:147], v[176:179], v[84:87]
	v_mfma_f32_16x16x32_bf16 v[80:83], v[152:155], v[176:179], v[80:83]
	v_mfma_f32_16x16x32_bf16 v[68:71], v[144:147], v[184:187], v[68:71]
	v_mfma_f32_16x16x32_bf16 v[64:67], v[152:155], v[184:187], v[64:67]
	v_mfma_f32_16x16x32_bf16 v[116:119], v[148:151], v[164:167], v[116:119]
	v_mfma_f32_16x16x32_bf16 v[108:111], v[156:159], v[164:167], v[108:111]
	v_mfma_f32_16x16x32_bf16 v[100:103], v[148:151], v[172:175], v[100:103]
	v_mfma_f32_16x16x32_bf16 v[92:95], v[156:159], v[172:175], v[92:95]
	v_mfma_f32_16x16x32_bf16 v[84:87], v[148:151], v[180:183], v[84:87]
	v_mfma_f32_16x16x32_bf16 v[80:83], v[156:159], v[180:183], v[80:83]
	v_mfma_f32_16x16x32_bf16 v[68:71], v[148:151], v[188:191], v[68:71]
	v_mfma_f32_16x16x32_bf16 v[64:67], v[156:159], v[188:191], v[64:67]
	s_setprio 0
	s_barrier
	s_add_i32 s51, s44, s33
	v_lshl_add_u64 v[192:193], s[24:25], 0, v[212:213]
	s_mov_b32 m0, s51
	ds_read_b128 v[160:163], v242 offset:16384
	ds_read_b128 v[164:167], v242 offset:17408
	ds_read_b128 v[168:171], v242 offset:18432
	ds_read_b128 v[172:175], v242 offset:19456
	ds_read_b128 v[176:179], v242 offset:20480
	ds_read_b128 v[180:183], v242 offset:21504
	ds_read_b128 v[184:187], v242 offset:22528
	ds_read_b128 v[188:191], v242 offset:23552
	global_load_lds_dwordx4 v[192:193], off
	s_add_i32 m0, s51, 0x2000
	s_add_u32 s52, s24, 0x40000
	v_lshl_add_u64 v[194:195], s[24:25], 0, v[216:217]
	s_addc_u32 s53, s25, 0
	s_add_i32 s51, s45, s33
	global_load_lds_dwordx4 v[194:195], off
	v_lshl_add_u64 v[196:197], s[52:53], 0, v[212:213]
	s_mov_b32 m0, s51
	v_lshl_add_u64 v[198:199], s[26:27], 0, v[214:215]
	global_load_lds_dwordx4 v[196:197], off
	v_lshl_add_u64 v[196:197], s[52:53], 0, v[216:217]
	s_add_i32 m0, s51, 0x2000
	s_nop 0
	global_load_lds_dwordx4 v[196:197], off
	v_lshl_add_u64 v[196:197], s[26:27], 0, v[210:211]
	s_mov_b32 m0, s34
	s_nop 0
	global_load_lds_dwordx4 v[196:197], off
	s_mov_b32 m0, s35
	s_nop 0
	global_load_lds_dwordx4 v[198:199], off
	s_waitcnt vmcnt(8)
	s_waitcnt lgkmcnt(0)
	s_barrier
	s_setprio 1
	s_waitcnt lgkmcnt(0)
	v_mfma_f32_16x16x32_bf16 v[60:63], v[128:131], v[160:163], v[60:63]
	v_mfma_f32_16x16x32_bf16 v[56:59], v[136:139], v[160:163], v[56:59]
	v_mfma_f32_16x16x32_bf16 v[48:51], v[128:131], v[168:171], v[48:51]
	v_mfma_f32_16x16x32_bf16 v[40:43], v[136:139], v[168:171], v[40:43]
	v_mfma_f32_16x16x32_bf16 v[32:35], v[128:131], v[176:179], v[32:35]
	v_mfma_f32_16x16x32_bf16 v[24:27], v[136:139], v[176:179], v[24:27]
	v_mfma_f32_16x16x32_bf16 v[12:15], v[128:131], v[184:187], v[12:15]
	v_mfma_f32_16x16x32_bf16 v[8:11], v[136:139], v[184:187], v[8:11]
	v_mfma_f32_16x16x32_bf16 v[60:63], v[132:135], v[164:167], v[60:63]
	v_mfma_f32_16x16x32_bf16 v[56:59], v[140:143], v[164:167], v[56:59]
	v_mfma_f32_16x16x32_bf16 v[48:51], v[132:135], v[172:175], v[48:51]
	v_mfma_f32_16x16x32_bf16 v[40:43], v[140:143], v[172:175], v[40:43]
	v_mfma_f32_16x16x32_bf16 v[32:35], v[132:135], v[180:183], v[32:35]
	v_mfma_f32_16x16x32_bf16 v[24:27], v[140:143], v[180:183], v[24:27]
	v_mfma_f32_16x16x32_bf16 v[12:15], v[132:135], v[188:191], v[12:15]
	v_mfma_f32_16x16x32_bf16 v[8:11], v[140:143], v[188:191], v[8:11]
	v_mfma_f32_16x16x32_bf16 v[52:55], v[144:147], v[160:163], v[52:55]
	v_mfma_f32_16x16x32_bf16 v[44:47], v[152:155], v[160:163], v[44:47]
	v_mfma_f32_16x16x32_bf16 v[36:39], v[144:147], v[168:171], v[36:39]
	v_mfma_f32_16x16x32_bf16 v[28:31], v[152:155], v[168:171], v[28:31]
	v_mfma_f32_16x16x32_bf16 v[20:23], v[144:147], v[176:179], v[20:23]
	v_mfma_f32_16x16x32_bf16 v[16:19], v[152:155], v[176:179], v[16:19]
	v_mfma_f32_16x16x32_bf16 v[4:7], v[144:147], v[184:187], v[4:7]
	v_mfma_f32_16x16x32_bf16 v[0:3], v[152:155], v[184:187], v[0:3]
	v_mfma_f32_16x16x32_bf16 v[52:55], v[148:151], v[164:167], v[52:55]
	v_mfma_f32_16x16x32_bf16 v[44:47], v[156:159], v[164:167], v[44:47]
	v_mfma_f32_16x16x32_bf16 v[36:39], v[148:151], v[172:175], v[36:39]
	v_mfma_f32_16x16x32_bf16 v[28:31], v[156:159], v[172:175], v[28:31]
	v_mfma_f32_16x16x32_bf16 v[20:23], v[148:151], v[180:183], v[20:23]
	v_mfma_f32_16x16x32_bf16 v[16:19], v[156:159], v[180:183], v[16:19]
	v_mfma_f32_16x16x32_bf16 v[4:7], v[148:151], v[188:191], v[4:7]
	v_mfma_f32_16x16x32_bf16 v[0:3], v[156:159], v[188:191], v[0:3]
	s_setprio 0
	s_barrier
	s_add_i32 s51, 0, 0x18000
	s_add_i32 s52, 0, 0x1c000
	v_add_u32_e32 v140, s51, v238
	v_add_u32_e32 v156, s52, v238
	ds_read_b128 v[128:131], v140
	ds_read_b128 v[132:135], v140 offset:1024
	ds_read_b128 v[136:139], v140 offset:2048
	ds_read_b128 v[140:143], v140 offset:3072
	ds_read_b128 v[144:147], v156
	ds_read_b128 v[148:151], v156 offset:1024
	ds_read_b128 v[152:155], v156 offset:2048
	ds_read_b128 v[156:159], v156 offset:3072
	s_add_u32 s26, s26, 0x40000
	s_addc_u32 s27, s27, 0
	s_mov_b32 m0, s36
	v_lshl_add_u64 v[200:201], s[26:27], 0, v[210:211]
	ds_read_b128 v[160:163], v242 offset:32768
	ds_read_b128 v[164:167], v242 offset:33792
	ds_read_b128 v[168:171], v242 offset:34816
	ds_read_b128 v[172:175], v242 offset:35840
	ds_read_b128 v[176:179], v242 offset:36864
	ds_read_b128 v[180:183], v242 offset:37888
	ds_read_b128 v[184:187], v242 offset:38912
	ds_read_b128 v[188:191], v242 offset:39936
	global_load_lds_dwordx4 v[200:201], off
	v_lshl_add_u64 v[200:201], s[26:27], 0, v[214:215]
	s_mov_b32 m0, s37
	s_nop 0
	global_load_lds_dwordx4 v[200:201], off
	s_waitcnt vmcnt(8)
	s_waitcnt lgkmcnt(0)
	s_barrier
	s_setprio 1
	s_waitcnt lgkmcnt(0)
	v_mfma_f32_16x16x32_bf16 v[124:127], v[128:131], v[160:163], v[124:127]
	v_mfma_f32_16x16x32_bf16 v[120:123], v[136:139], v[160:163], v[120:123]
	v_mfma_f32_16x16x32_bf16 v[112:115], v[128:131], v[168:171], v[112:115]
	v_mfma_f32_16x16x32_bf16 v[104:107], v[136:139], v[168:171], v[104:107]
	v_mfma_f32_16x16x32_bf16 v[96:99], v[128:131], v[176:179], v[96:99]
	v_mfma_f32_16x16x32_bf16 v[88:91], v[136:139], v[176:179], v[88:91]
	v_mfma_f32_16x16x32_bf16 v[76:79], v[128:131], v[184:187], v[76:79]
	v_mfma_f32_16x16x32_bf16 v[72:75], v[136:139], v[184:187], v[72:75]
	v_mfma_f32_16x16x32_bf16 v[124:127], v[132:135], v[164:167], v[124:127]
	v_mfma_f32_16x16x32_bf16 v[120:123], v[140:143], v[164:167], v[120:123]
	v_mfma_f32_16x16x32_bf16 v[112:115], v[132:135], v[172:175], v[112:115]
	v_mfma_f32_16x16x32_bf16 v[104:107], v[140:143], v[172:175], v[104:107]
	v_mfma_f32_16x16x32_bf16 v[96:99], v[132:135], v[180:183], v[96:99]
	v_mfma_f32_16x16x32_bf16 v[88:91], v[140:143], v[180:183], v[88:91]
	v_mfma_f32_16x16x32_bf16 v[76:79], v[132:135], v[188:191], v[76:79]
	v_mfma_f32_16x16x32_bf16 v[72:75], v[140:143], v[188:191], v[72:75]
	v_mfma_f32_16x16x32_bf16 v[116:119], v[144:147], v[160:163], v[116:119]
	v_mfma_f32_16x16x32_bf16 v[108:111], v[152:155], v[160:163], v[108:111]
	v_mfma_f32_16x16x32_bf16 v[100:103], v[144:147], v[168:171], v[100:103]
	v_mfma_f32_16x16x32_bf16 v[92:95], v[152:155], v[168:171], v[92:95]
	v_mfma_f32_16x16x32_bf16 v[84:87], v[144:147], v[176:179], v[84:87]
	v_mfma_f32_16x16x32_bf16 v[80:83], v[152:155], v[176:179], v[80:83]
	v_mfma_f32_16x16x32_bf16 v[68:71], v[144:147], v[184:187], v[68:71]
	v_mfma_f32_16x16x32_bf16 v[64:67], v[152:155], v[184:187], v[64:67]
	v_mfma_f32_16x16x32_bf16 v[116:119], v[148:151], v[164:167], v[116:119]
	v_mfma_f32_16x16x32_bf16 v[108:111], v[156:159], v[164:167], v[108:111]
	v_mfma_f32_16x16x32_bf16 v[100:103], v[148:151], v[172:175], v[100:103]
	v_mfma_f32_16x16x32_bf16 v[92:95], v[156:159], v[172:175], v[92:95]
	v_mfma_f32_16x16x32_bf16 v[84:87], v[148:151], v[180:183], v[84:87]
	v_mfma_f32_16x16x32_bf16 v[80:83], v[156:159], v[180:183], v[80:83]
	v_mfma_f32_16x16x32_bf16 v[68:71], v[148:151], v[188:191], v[68:71]
	v_mfma_f32_16x16x32_bf16 v[64:67], v[156:159], v[188:191], v[64:67]
	s_setprio 0
	s_barrier
	s_add_i32 s26, s51, s33
	v_lshl_add_u64 v[192:193], v[192:193], 0, s[12:13]
	s_mov_b32 m0, s26
	ds_read_b128 v[160:163], v242 offset:49152
	ds_read_b128 v[164:167], v242 offset:50176
	ds_read_b128 v[168:171], v242 offset:51200
	ds_read_b128 v[172:175], v242 offset:52224
	ds_read_b128 v[176:179], v242 offset:53248
	ds_read_b128 v[180:183], v242 offset:54272
	ds_read_b128 v[184:187], v242 offset:55296
	ds_read_b128 v[188:191], v242 offset:56320
	global_load_lds_dwordx4 v[192:193], off
	s_add_i32 m0, s26, 0x2000
	s_add_u32 s24, s24, 0x40080
	v_lshl_add_u64 v[192:193], v[194:195], 0, s[12:13]
	s_addc_u32 s25, s25, 0
	s_add_i32 s26, s52, s33
	global_load_lds_dwordx4 v[192:193], off
	v_lshl_add_u64 v[192:193], s[24:25], 0, v[212:213]
	s_mov_b32 m0, s26
	s_nop 0
	global_load_lds_dwordx4 v[192:193], off
	v_lshl_add_u64 v[192:193], s[24:25], 0, v[216:217]
	s_add_i32 m0, s26, 0x2000
	s_nop 0
	global_load_lds_dwordx4 v[192:193], off
	v_lshl_add_u64 v[192:193], v[196:197], 0, s[12:13]
	s_mov_b32 m0, s39
	s_nop 0
	global_load_lds_dwordx4 v[192:193], off
	v_lshl_add_u64 v[192:193], v[198:199], 0, s[12:13]
	s_mov_b32 m0, s40
	s_nop 0
	global_load_lds_dwordx4 v[192:193], off
	s_waitcnt vmcnt(8)
	s_waitcnt lgkmcnt(0)
	s_barrier
	s_setprio 1
	s_waitcnt lgkmcnt(0)
	v_mfma_f32_16x16x32_bf16 v[60:63], v[128:131], v[160:163], v[60:63]
	v_mfma_f32_16x16x32_bf16 v[56:59], v[136:139], v[160:163], v[56:59]
	v_mfma_f32_16x16x32_bf16 v[48:51], v[128:131], v[168:171], v[48:51]
	v_mfma_f32_16x16x32_bf16 v[40:43], v[136:139], v[168:171], v[40:43]
	v_mfma_f32_16x16x32_bf16 v[32:35], v[128:131], v[176:179], v[32:35]
	v_mfma_f32_16x16x32_bf16 v[24:27], v[136:139], v[176:179], v[24:27]
	v_mfma_f32_16x16x32_bf16 v[12:15], v[128:131], v[184:187], v[12:15]
	v_mfma_f32_16x16x32_bf16 v[8:11], v[136:139], v[184:187], v[8:11]
	v_mfma_f32_16x16x32_bf16 v[60:63], v[132:135], v[164:167], v[60:63]
	v_mfma_f32_16x16x32_bf16 v[56:59], v[140:143], v[164:167], v[56:59]
	v_mfma_f32_16x16x32_bf16 v[48:51], v[132:135], v[172:175], v[48:51]
	v_mfma_f32_16x16x32_bf16 v[40:43], v[140:143], v[172:175], v[40:43]
	v_mfma_f32_16x16x32_bf16 v[32:35], v[132:135], v[180:183], v[32:35]
	v_mfma_f32_16x16x32_bf16 v[24:27], v[140:143], v[180:183], v[24:27]
	v_mfma_f32_16x16x32_bf16 v[12:15], v[132:135], v[188:191], v[12:15]
	v_mfma_f32_16x16x32_bf16 v[8:11], v[140:143], v[188:191], v[8:11]
	v_mfma_f32_16x16x32_bf16 v[52:55], v[144:147], v[160:163], v[52:55]
	v_mfma_f32_16x16x32_bf16 v[44:47], v[152:155], v[160:163], v[44:47]
	v_mfma_f32_16x16x32_bf16 v[36:39], v[144:147], v[168:171], v[36:39]
	v_mfma_f32_16x16x32_bf16 v[28:31], v[152:155], v[168:171], v[28:31]
	v_mfma_f32_16x16x32_bf16 v[20:23], v[144:147], v[176:179], v[20:23]
	v_mfma_f32_16x16x32_bf16 v[16:19], v[152:155], v[176:179], v[16:19]
	v_mfma_f32_16x16x32_bf16 v[4:7], v[144:147], v[184:187], v[4:7]
	v_mfma_f32_16x16x32_bf16 v[0:3], v[152:155], v[184:187], v[0:3]
	v_mfma_f32_16x16x32_bf16 v[52:55], v[148:151], v[164:167], v[52:55]
	v_mfma_f32_16x16x32_bf16 v[44:47], v[156:159], v[164:167], v[44:47]
	v_mfma_f32_16x16x32_bf16 v[36:39], v[148:151], v[172:175], v[36:39]
	v_mfma_f32_16x16x32_bf16 v[28:31], v[156:159], v[172:175], v[28:31]
	v_mfma_f32_16x16x32_bf16 v[20:23], v[148:151], v[180:183], v[20:23]
	v_mfma_f32_16x16x32_bf16 v[16:19], v[156:159], v[180:183], v[16:19]
	v_mfma_f32_16x16x32_bf16 v[4:7], v[148:151], v[188:191], v[4:7]
	v_mfma_f32_16x16x32_bf16 v[0:3], v[156:159], v[188:191], v[0:3]
	s_setprio 0
	s_barrier
	s_add_i32 s50, s50, 2
	s_add_u32 s22, s22, 0x100
	s_addc_u32 s23, s23, 0
	s_add_u32 s48, s48, 0x100
	s_addc_u32 s49, s49, 0
	s_cmp_gt_u32 s50, 13
	s_cbranch_scc0 .LBB0_1028
	s_cmpk_lg_i32 s78, 0x100
	s_cbranch_scc1 .Lepi8_orig
	s_nop 7
	s_nop 7
	v_and_b32_e32 v228, 15, v236
	v_lshrrev_b32_e32 v229, 8, v236
	v_lshl_add_u32 v228, v229, 6, v228
	v_lshlrev_b32_e32 v228, 12, v228
	v_bfe_u32 v229, v236, 6, 2
	v_bfe_u32 v230, v236, 4, 2
	v_lshlrev_b32_e32 v229, 7, v229
	v_lshl_or_b32 v229, v230, 5, v229
	v_add_u32_e32 v228, v228, v229
	s_lshr_b32 vcc_lo, s4, 3
	s_mul_i32 vcc_lo, vcc_lo, 0x9000
	s_lshl_b32 vcc_hi, s5, 10
	s_add_i32 vcc_lo, vcc_lo, vcc_hi
	s_add_u32 s98, s74, 0x5000
	s_addc_u32 s99, s75, 0
	s_add_u32 s98, s98, vcc_lo
	s_addc_u32 s99, s99, 0
	global_load_dwordx4 v[210:213], v229, s[98:99]
	global_load_dwordx4 v[214:217], v229, s[98:99] offset:16
	global_load_dwordx4 v[218:221], v229, s[98:99] offset:512
	global_load_dwordx4 v[222:225], v229, s[98:99] offset:528
	s_lshl_b32 vcc_lo, s4, 20
	s_add_i32 vcc_lo, vcc_lo, vcc_hi
	s_add_u32 s98, s72, vcc_lo
	s_addc_u32 s99, s73, 0
	s_add_u32 s100, s72, vcc_lo
	s_addc_u32 s101, s73, 0
	global_load_dwordx4 v[128:131], v228, s[98:99]
	global_load_dwordx4 v[132:135], v228, s[98:99] offset:16
	global_load_dwordx4 v[136:139], v228, s[98:99] offset:512
	global_load_dwordx4 v[140:143], v228, s[98:99] offset:528
	s_add_u32 s98, s98, 0x10000
	s_addc_u32 s99, s99, 0
	global_load_dwordx4 v[144:147], v228, s[98:99]
	global_load_dwordx4 v[148:151], v228, s[98:99] offset:16
	global_load_dwordx4 v[152:155], v228, s[98:99] offset:512
	global_load_dwordx4 v[156:159], v228, s[98:99] offset:528
	s_add_u32 s98, s98, 0x10000
	s_addc_u32 s99, s99, 0
	global_load_dwordx4 v[160:163], v228, s[98:99]
	global_load_dwordx4 v[164:167], v228, s[98:99] offset:16
	global_load_dwordx4 v[168:171], v228, s[98:99] offset:512
	global_load_dwordx4 v[172:175], v228, s[98:99] offset:528
	s_add_u32 s98, s98, 0x10000
	s_addc_u32 s99, s99, 0
	global_load_dwordx4 v[176:179], v228, s[98:99]
	global_load_dwordx4 v[180:183], v228, s[98:99] offset:16
	global_load_dwordx4 v[184:187], v228, s[98:99] offset:512
	global_load_dwordx4 v[188:191], v228, s[98:99] offset:528
	s_add_u32 s98, s98, 0x50000
	s_addc_u32 s99, s99, 0
	global_load_dwordx4 v[192:195], v228, s[98:99]
	global_load_dwordx4 v[196:199], v228, s[98:99] offset:16
	global_load_dwordx4 v[200:203], v228, s[98:99] offset:512
	global_load_dwordx4 v[204:207], v228, s[98:99] offset:528
	s_add_u32 s98, s98, 0x10000
	s_addc_u32 s99, s99, 0
	s_waitcnt vmcnt(16)
	v_pk_fma_f32 v[124:125], v[124:125], v[210:211], v[128:129]
	v_pk_fma_f32 v[126:127], v[126:127], v[212:213], v[130:131]
	v_pk_fma_f32 v[120:121], v[120:121], v[214:215], v[132:133]
	v_pk_fma_f32 v[122:123], v[122:123], v[216:217], v[134:135]
	v_pk_fma_f32 v[116:117], v[116:117], v[218:219], v[136:137]
	v_pk_fma_f32 v[118:119], v[118:119], v[220:221], v[138:139]
	v_pk_fma_f32 v[108:109], v[108:109], v[222:223], v[140:141]
	v_pk_fma_f32 v[110:111], v[110:111], v[224:225], v[142:143]
	global_store_dwordx4 v228, v[124:127], s[100:101]
	global_store_dwordx4 v228, v[120:123], s[100:101] offset:16
	global_store_dwordx4 v228, v[116:119], s[100:101] offset:512
	global_store_dwordx4 v228, v[108:111], s[100:101] offset:528
	s_add_u32 s100, s100, 0x10000
	s_addc_u32 s101, s101, 0
	global_load_dwordx4 v[128:131], v228, s[98:99]
	global_load_dwordx4 v[132:135], v228, s[98:99] offset:16
	global_load_dwordx4 v[136:139], v228, s[98:99] offset:512
	global_load_dwordx4 v[140:143], v228, s[98:99] offset:528
	s_add_u32 s98, s98, 0x10000
	s_addc_u32 s99, s99, 0
	s_waitcnt vmcnt(20)
	v_pk_fma_f32 v[112:113], v[112:113], v[210:211], v[144:145]
	v_pk_fma_f32 v[114:115], v[114:115], v[212:213], v[146:147]
	v_pk_fma_f32 v[104:105], v[104:105], v[214:215], v[148:149]
	v_pk_fma_f32 v[106:107], v[106:107], v[216:217], v[150:151]
	v_pk_fma_f32 v[100:101], v[100:101], v[218:219], v[152:153]
	v_pk_fma_f32 v[102:103], v[102:103], v[220:221], v[154:155]
	v_pk_fma_f32 v[92:93], v[92:93], v[222:223], v[156:157]
	v_pk_fma_f32 v[94:95], v[94:95], v[224:225], v[158:159]
	global_store_dwordx4 v228, v[112:115], s[100:101]
	global_store_dwordx4 v228, v[104:107], s[100:101] offset:16
	global_store_dwordx4 v228, v[100:103], s[100:101] offset:512
	global_store_dwordx4 v228, v[92:95], s[100:101] offset:528
	s_add_u32 s100, s100, 0x10000
	s_addc_u32 s101, s101, 0
	global_load_dwordx4 v[144:147], v228, s[98:99]
	global_load_dwordx4 v[148:151], v228, s[98:99] offset:16
	global_load_dwordx4 v[152:155], v228, s[98:99] offset:512
	global_load_dwordx4 v[156:159], v228, s[98:99] offset:528
	s_add_u32 s98, s98, 0x10000
	s_addc_u32 s99, s99, 0
	s_waitcnt vmcnt(24)
	v_pk_fma_f32 v[96:97], v[96:97], v[210:211], v[160:161]
	v_pk_fma_f32 v[98:99], v[98:99], v[212:213], v[162:163]
	v_pk_fma_f32 v[88:89], v[88:89], v[214:215], v[164:165]
	v_pk_fma_f32 v[90:91], v[90:91], v[216:217], v[166:167]
	v_pk_fma_f32 v[84:85], v[84:85], v[218:219], v[168:169]
	v_pk_fma_f32 v[86:87], v[86:87], v[220:221], v[170:171]
	v_pk_fma_f32 v[80:81], v[80:81], v[222:223], v[172:173]
	v_pk_fma_f32 v[82:83], v[82:83], v[224:225], v[174:175]
	global_store_dwordx4 v228, v[96:99], s[100:101]
	global_store_dwordx4 v228, v[88:91], s[100:101] offset:16
	global_store_dwordx4 v228, v[84:87], s[100:101] offset:512
	global_store_dwordx4 v228, v[80:83], s[100:101] offset:528
	s_add_u32 s100, s100, 0x10000
	s_addc_u32 s101, s101, 0
	global_load_dwordx4 v[160:163], v228, s[98:99]
	global_load_dwordx4 v[164:167], v228, s[98:99] offset:16
	global_load_dwordx4 v[168:171], v228, s[98:99] offset:512
	global_load_dwordx4 v[172:175], v228, s[98:99] offset:528
	s_waitcnt vmcnt(28)
	v_pk_fma_f32 v[76:77], v[76:77], v[210:211], v[176:177]
	v_pk_fma_f32 v[78:79], v[78:79], v[212:213], v[178:179]
	v_pk_fma_f32 v[72:73], v[72:73], v[214:215], v[180:181]
	v_pk_fma_f32 v[74:75], v[74:75], v[216:217], v[182:183]
	v_pk_fma_f32 v[68:69], v[68:69], v[218:219], v[184:185]
	v_pk_fma_f32 v[70:71], v[70:71], v[220:221], v[186:187]
	v_pk_fma_f32 v[64:65], v[64:65], v[222:223], v[188:189]
	v_pk_fma_f32 v[66:67], v[66:67], v[224:225], v[190:191]
	global_store_dwordx4 v228, v[76:79], s[100:101]
	global_store_dwordx4 v228, v[72:75], s[100:101] offset:16
	global_store_dwordx4 v228, v[68:71], s[100:101] offset:512
	global_store_dwordx4 v228, v[64:67], s[100:101] offset:528
	s_add_u32 s100, s100, 0x50000
	s_addc_u32 s101, s101, 0
	s_waitcnt vmcnt(28)
	v_pk_fma_f32 v[60:61], v[60:61], v[210:211], v[192:193]
	v_pk_fma_f32 v[62:63], v[62:63], v[212:213], v[194:195]
	v_pk_fma_f32 v[56:57], v[56:57], v[214:215], v[196:197]
	v_pk_fma_f32 v[58:59], v[58:59], v[216:217], v[198:199]
	v_pk_fma_f32 v[52:53], v[52:53], v[218:219], v[200:201]
	v_pk_fma_f32 v[54:55], v[54:55], v[220:221], v[202:203]
	v_pk_fma_f32 v[44:45], v[44:45], v[222:223], v[204:205]
	v_pk_fma_f32 v[46:47], v[46:47], v[224:225], v[206:207]
	global_store_dwordx4 v228, v[60:63], s[100:101]
	global_store_dwordx4 v228, v[56:59], s[100:101] offset:16
	global_store_dwordx4 v228, v[52:55], s[100:101] offset:512
	global_store_dwordx4 v228, v[44:47], s[100:101] offset:528
	s_add_u32 s100, s100, 0x10000
	s_addc_u32 s101, s101, 0
	s_waitcnt vmcnt(24)
	v_pk_fma_f32 v[48:49], v[48:49], v[210:211], v[128:129]
	v_pk_fma_f32 v[50:51], v[50:51], v[212:213], v[130:131]
	v_pk_fma_f32 v[40:41], v[40:41], v[214:215], v[132:133]
	v_pk_fma_f32 v[42:43], v[42:43], v[216:217], v[134:135]
	v_pk_fma_f32 v[36:37], v[36:37], v[218:219], v[136:137]
	v_pk_fma_f32 v[38:39], v[38:39], v[220:221], v[138:139]
	v_pk_fma_f32 v[28:29], v[28:29], v[222:223], v[140:141]
	v_pk_fma_f32 v[30:31], v[30:31], v[224:225], v[142:143]
	global_store_dwordx4 v228, v[48:51], s[100:101]
	global_store_dwordx4 v228, v[40:43], s[100:101] offset:16
	global_store_dwordx4 v228, v[36:39], s[100:101] offset:512
	global_store_dwordx4 v228, v[28:31], s[100:101] offset:528
	s_add_u32 s100, s100, 0x10000
	s_addc_u32 s101, s101, 0
	s_waitcnt vmcnt(20)
	v_pk_fma_f32 v[32:33], v[32:33], v[210:211], v[144:145]
	v_pk_fma_f32 v[34:35], v[34:35], v[212:213], v[146:147]
	v_pk_fma_f32 v[24:25], v[24:25], v[214:215], v[148:149]
	v_pk_fma_f32 v[26:27], v[26:27], v[216:217], v[150:151]
	v_pk_fma_f32 v[20:21], v[20:21], v[218:219], v[152:153]
	v_pk_fma_f32 v[22:23], v[22:23], v[220:221], v[154:155]
	v_pk_fma_f32 v[16:17], v[16:17], v[222:223], v[156:157]
	v_pk_fma_f32 v[18:19], v[18:19], v[224:225], v[158:159]
	global_store_dwordx4 v228, v[32:35], s[100:101]
	global_store_dwordx4 v228, v[24:27], s[100:101] offset:16
	global_store_dwordx4 v228, v[20:23], s[100:101] offset:512
	global_store_dwordx4 v228, v[16:19], s[100:101] offset:528
	s_add_u32 s100, s100, 0x10000
	s_addc_u32 s101, s101, 0
	s_waitcnt vmcnt(16)
	v_pk_fma_f32 v[12:13], v[12:13], v[210:211], v[160:161]
	v_pk_fma_f32 v[14:15], v[14:15], v[212:213], v[162:163]
	v_pk_fma_f32 v[8:9], v[8:9], v[214:215], v[164:165]
	v_pk_fma_f32 v[10:11], v[10:11], v[216:217], v[166:167]
	v_pk_fma_f32 v[4:5], v[4:5], v[218:219], v[168:169]
	v_pk_fma_f32 v[6:7], v[6:7], v[220:221], v[170:171]
	v_pk_fma_f32 v[0:1], v[0:1], v[222:223], v[172:173]
	v_pk_fma_f32 v[2:3], v[2:3], v[224:225], v[174:175]
	global_store_dwordx4 v228, v[12:15], s[100:101]
	global_store_dwordx4 v228, v[8:11], s[100:101] offset:16
	global_store_dwordx4 v228, v[4:7], s[100:101] offset:512
	global_store_dwordx4 v228, v[0:3], s[100:101] offset:528
	s_branch .LBB0_1037
.Lepi8_orig:
	s_cmp_gt_i32 s4, 63
	v_lshl_or_b32 v128, s5, 8, v239
	s_cselect_b64 s[22:23], -1, 0
	s_lshl_b32 s5, s4, 2
	s_add_i32 s17, s41, s5
	s_ashr_i32 s15, s4, 3
	s_cmp_lt_i32 s4, 64
	v_lshl_add_u32 v228, s4, 8, v237
	s_cselect_b64 s[4:5], -1, 0
	v_add_u32_e32 v130, 0xffffc000, v228
	s_and_b64 vcc, s[4:5], exec
	v_cndmask_b32_e64 v144, v130, v228, s[4:5]
	s_cselect_b32 s24, s15, s17
	s_mul_i32 s26, s24, 0x9000
	v_ashrrev_i32_e32 v145, 31, v144
	v_ashrrev_i32_e32 v129, 31, v128
	s_mul_hi_i32 s27, s24, 0x9000
	s_cselect_b32 s25, s73, s7
	s_cselect_b32 s24, s72, s6
	s_add_u32 s26, s10, s26
	v_lshlrev_b64 v[144:145], 12, v[144:145]
	s_addc_u32 s27, s11, s27
	v_lshlrev_b64 v[226:227], 2, v[128:129]
	v_lshl_add_u64 v[144:145], s[24:25], 0, v[144:145]
	v_lshl_add_u64 v[136:137], s[26:27], 0, v[226:227]
	v_lshl_add_u64 v[144:145], v[144:145], 0, v[226:227]
	global_load_dwordx4 v[132:135], v[136:137], off offset:16
	global_load_dwordx4 v[140:143], v[136:137], off
	global_load_dwordx4 v[128:131], v[136:137], off offset:528
	s_nop 0
	global_load_dwordx4 v[136:139], v[136:137], off offset:512
	s_nop 0
	global_load_dwordx4 v[200:203], v[144:145], off offset:16
	global_load_dwordx4 v[204:207], v[144:145], off
	global_load_dwordx4 v[192:195], v[144:145], off offset:528
	global_load_dwordx4 v[196:199], v[144:145], off offset:512
	v_or_b32_e32 v230, 16, v228
	v_add_u32_e32 v144, 0xffffc010, v228
	v_cndmask_b32_e64 v144, v144, v230, s[4:5]
	v_ashrrev_i32_e32 v145, 31, v144
	v_lshlrev_b64 v[144:145], 12, v[144:145]
	v_lshl_add_u64 v[144:145], s[24:25], 0, v[144:145]
	v_lshl_add_u64 v[144:145], v[144:145], 0, v[226:227]
	global_load_dwordx4 v[184:187], v[144:145], off offset:16
	global_load_dwordx4 v[188:191], v[144:145], off
	global_load_dwordx4 v[176:179], v[144:145], off offset:528
	global_load_dwordx4 v[180:183], v[144:145], off offset:512
	v_or_b32_e32 v232, 32, v228
	v_add_u32_e32 v144, 0xffffc020, v228
	v_cndmask_b32_e64 v144, v144, v232, s[4:5]
	v_ashrrev_i32_e32 v145, 31, v144
	v_lshlrev_b64 v[144:145], 12, v[144:145]
	v_lshl_add_u64 v[144:145], s[24:25], 0, v[144:145]
	v_lshl_add_u64 v[144:145], v[144:145], 0, v[226:227]
	global_load_dwordx4 v[168:171], v[144:145], off offset:16
	global_load_dwordx4 v[172:175], v[144:145], off
	global_load_dwordx4 v[160:163], v[144:145], off offset:528
	global_load_dwordx4 v[164:167], v[144:145], off offset:512
	v_or_b32_e32 v146, 48, v228
	s_mov_b64 s[26:27], -1
	v_ashrrev_i32_e32 v147, 31, v146
	s_cbranch_vccnz .LBB0_1031
	v_add_u32_e32 v144, 0xffffc030, v228
	v_ashrrev_i32_e32 v145, 31, v144
	v_lshlrev_b64 v[144:145], 12, v[144:145]
	v_lshl_add_u64 v[144:145], s[6:7], 0, v[144:145]
	v_lshlrev_b64 v[234:235], 12, v[146:147]
	s_mov_b64 s[26:27], 0

	.amdhsa_kernel _Z8fwd_mega4Args
		.amdhsa_group_segment_fixed_size 0
		.amdhsa_private_segment_fixed_size 0
		.amdhsa_kernarg_size 456
		.amdhsa_user_sgpr_count 2
		.amdhsa_user_sgpr_dispatch_ptr 0
		.amdhsa_user_sgpr_queue_ptr 0
		.amdhsa_user_sgpr_kernarg_segment_ptr 1
		.amdhsa_user_sgpr_dispatch_id 0
		.amdhsa_user_sgpr_kernarg_preload_length 0
		.amdhsa_user_sgpr_kernarg_preload_offset 0
		.amdhsa_user_sgpr_private_segment_size 0
		.amdhsa_uses_dynamic_stack 0
		.amdhsa_enable_private_segment 0
		.amdhsa_system_sgpr_workgroup_id_x 1
		.amdhsa_system_sgpr_workgroup_id_y 0
		.amdhsa_system_sgpr_workgroup_id_z 0
		.amdhsa_system_sgpr_workgroup_info 0
		.amdhsa_system_vgpr_workitem_id 2
		.amdhsa_next_free_vgpr 247
		.amdhsa_next_free_sgpr 102
		.amdhsa_accum_offset 248
		.amdhsa_reserve_vcc 1
		.amdhsa_float_round_mode_32 0
		.amdhsa_float_round_mode_16_64 0
		.amdhsa_float_denorm_mode_32 3
		.amdhsa_float_denorm_mode_16_64 3
		.amdhsa_dx10_clamp 1
		.amdhsa_ieee_mode 1
		.amdhsa_fp16_overflow 0
		.amdhsa_tg_split 0
		.amdhsa_exception_fp_ieee_invalid_op 0
		.amdhsa_exception_fp_denorm_src 0
		.amdhsa_exception_fp_ieee_div_zero 0
		.amdhsa_exception_fp_ieee_overflow 0
		.amdhsa_exception_fp_ieee_underflow 0
		.amdhsa_exception_fp_ieee_inexact 0
		.amdhsa_exception_int_div_zero 0
	.end_amdhsa_kernel

amdhsa.kernels:
  - .agpr_count:     0
    .args:
      - .offset:         0
        .size:           200
        .value_kind:     by_value
      - .offset:         200
        .size:           4
        .value_kind:     hidden_block_count_x
      - .offset:         204
        .size:           4
        .value_kind:     hidden_block_count_y
      - .offset:         208
        .size:           4
        .value_kind:     hidden_block_count_z
      - .offset:         212
        .size:           2
        .value_kind:     hidden_group_size_x
      - .offset:         214
        .size:           2
        .value_kind:     hidden_group_size_y
      - .offset:         216
        .size:           2
        .value_kind:     hidden_group_size_z
      - .offset:         218
        .size:           2
        .value_kind:     hidden_remainder_x
      - .offset:         220
        .size:           2
        .value_kind:     hidden_remainder_y
      - .offset:         222
        .size:           2
        .value_kind:     hidden_remainder_z
      - .offset:         240
        .size:           8
        .value_kind:     hidden_global_offset_x
      - .offset:         248
        .size:           8
        .value_kind:     hidden_global_offset_y
      - .offset:         256
        .size:           8
        .value_kind:     hidden_global_offset_z
      - .offset:         264
        .size:           2
        .value_kind:     hidden_grid_dims
      - .offset:         288
        .size:           8
        .value_kind:     hidden_multigrid_sync_arg
      - .offset:         320
        .size:           4
        .value_kind:     hidden_dynamic_lds_size
    .group_segment_fixed_size: 0
    .kernarg_segment_align: 8
    .kernarg_segment_size: 456
    .language:       OpenCL C
    .language_version:
      - 2
      - 0
    .max_flat_workgroup_size: 512
    .name:           _Z8fwd_mega4Args
    .private_segment_fixed_size: 0
    .sgpr_count:     108
    .sgpr_spill_count: 109
    .symbol:         _Z8fwd_mega4Args.kd
    .uniform_work_group_size: 1
    .uses_dynamic_stack: false
    .vgpr_count:     247
    .vgpr_spill_count: 0
    .wavefront_size: 64
